# speedup vs baseline: 1.0007x; 1.0007x over previous
; #define WAIT_V(n) asm volatile("s_waitcnt vmcnt(%0)" ::"n"(n) : "memory")
; #define SCHED() __builtin_amdgcn_sched_barrier(0)
; #define LGKM(n) asm volatile("s_waitcnt lgkmcnt(%0)" ::"n"(n) : "memory")
; #define STAGE_A(b, h, kt) STAGE_AX(Ag, b, h, kt)
; #define STAGE_B(b, h, kt) STAGE_BX(Bg, b, h, kt)
; #define LDA(b, h) do { const unsigned pa_ = lds0 + SLOTA(b, h) + wr * 8192 + laneoff; _Pragma("unroll") for (int m = 0; m < 4; ++m)   \
;       _Pragma("unroll") for (int k = 0; k < 2; ++k) DSR(At[m][k], pa_, m * 2048 + k * 1024); } while (0)
; #define LDB(dst, b, h) do { const unsigned pb_ = lds0 + SLOTB(b, h) + wc * 4096 + laneoff; _Pragma("unroll") for (int n = 0; n < 2; ++n) \
;       _Pragma("unroll") for (int k = 0; k < 2; ++k) DSR(dst[n][k], pb_, n * 2048 + k * 1024); } while (0)
; #define BAR __builtin_amdgcn_s_barrier()
; #define LGKM(n) asm volatile("s_waitcnt lgkmcnt(%0)" ::"n"(n) : "memory")
; template <int EPI, bool SWP> ...
;     ...
;   for (int t = 0; t < nt - 2; t += 2) {
;     LDB(B0, 0, 0); LDA(0, 0); STAGE_A(1, 1, t + 1);
;     LGKM(8); BAR; LGKM(0); SCHED(); MMA(0, 0, B0); BAR; SCHED();
;     LDB(B1, 0, 1); STAGE_B(0, 0, t + 2);
;     BAR; LGKM(0); SCHED(); MMA(0, 1, B1); BAR; SCHED();
;     LDA(0, 1); STAGE_A(0, 0, t + 2);
;     BAR; LGKM(0); SCHED(); MMA(1, 0, B0); BAR; SCHED();
;     STAGE_B(0, 1, t + 2);
;     WAIT_V(6); BAR; SCHED(); MMA(1, 1, B1); BAR; SCHED();
.LBB0_81:
	ds_read_b128 v[128:131], v219 offset:0
	ds_read_b128 v[132:135], v219 offset:0x400
	ds_read_b128 v[136:139], v219 offset:0x800
	ds_read_b128 v[140:143], v219 offset:0xc00
	ds_read_b128 v[144:147], v220 offset:0
	ds_read_b128 v[148:151], v220 offset:0x400
	ds_read_b128 v[152:155], v220 offset:0x800
	ds_read_b128 v[156:159], v220 offset:0xc00
	ds_read_b128 v[160:163], v220 offset:0x1000
	ds_read_b128 v[164:167], v220 offset:0x1400
	ds_read_b128 v[168:171], v220 offset:0x1800
	v_lshl_add_u64 v[192:193], s[76:77], 0, v[210:211]
	s_mov_b32 m0, s79
	ds_read_b128 v[172:175], v220 offset:0x1c00
	s_add_u32 s94, s76, s44
	s_addc_u32 s95, s77, s45
	global_load_lds_dwordx4 v210, s[94:95]
	s_mov_b32 m0, s80
	s_add_u32 s94, s76, s48
	s_addc_u32 s95, s77, s49
	global_load_lds_dwordx4 v210, s[94:95]
	s_waitcnt lgkmcnt(8)
	s_barrier
	s_waitcnt lgkmcnt(0)
	v_mfma_f32_16x16x32_bf16 v[124:127], v[128:131], v[144:147], v[124:127]
	v_mfma_f32_16x16x32_bf16 v[120:123], v[136:139], v[144:147], v[120:123]
	v_mfma_f32_16x16x32_bf16 v[116:119], v[128:131], v[152:155], v[116:119]
	v_mfma_f32_16x16x32_bf16 v[112:115], v[136:139], v[152:155], v[112:115]
	v_mfma_f32_16x16x32_bf16 v[108:111], v[128:131], v[160:163], v[108:111]
	v_mfma_f32_16x16x32_bf16 v[104:107], v[136:139], v[160:163], v[104:107]
	v_mfma_f32_16x16x32_bf16 v[100:103], v[128:131], v[168:171], v[100:103]
	v_mfma_f32_16x16x32_bf16 v[96:99], v[136:139], v[168:171], v[96:99]
	v_mfma_f32_16x16x32_bf16 v[124:127], v[132:135], v[148:151], v[124:127]
	v_mfma_f32_16x16x32_bf16 v[120:123], v[140:143], v[148:151], v[120:123]
	v_mfma_f32_16x16x32_bf16 v[116:119], v[132:135], v[156:159], v[116:119]
	v_mfma_f32_16x16x32_bf16 v[112:115], v[140:143], v[156:159], v[112:115]
	v_mfma_f32_16x16x32_bf16 v[108:111], v[132:135], v[164:167], v[108:111]
	v_mfma_f32_16x16x32_bf16 v[104:107], v[140:143], v[164:167], v[104:107]
	v_mfma_f32_16x16x32_bf16 v[100:103], v[132:135], v[172:175], v[100:103]
	v_mfma_f32_16x16x32_bf16 v[96:99], v[140:143], v[172:175], v[96:99]
	s_barrier
	ds_read_b128 v[176:179], v221 offset:0
	ds_read_b128 v[180:183], v221 offset:0x400
	ds_read_b128 v[184:187], v221 offset:0x800
	v_lshl_add_u64 v[194:195], s[74:75], 0, v[210:211]
	s_mov_b64 s[84:85], 0x30100100
	s_mov_b32 m0, s19
	ds_read_b128 v[188:191], v221 offset:0xc00
	s_mov_b64 s[84:85], 0x30140100
	s_add_u32 s94, s74, 0x30100100
	s_addc_u32 s95, s75, 0
	global_load_lds_dwordx4 v210, s[94:95]
	s_mov_b32 m0, s30
	s_add_u32 s94, s74, 0x30140100
	s_addc_u32 s95, s75, 0
	global_load_lds_dwordx4 v210, s[94:95]
	s_barrier
	s_waitcnt lgkmcnt(0)
	v_mfma_f32_16x16x32_bf16 v[92:95], v[176:179], v[144:147], v[92:95]
	v_mfma_f32_16x16x32_bf16 v[88:91], v[184:187], v[144:147], v[88:91]
	v_mfma_f32_16x16x32_bf16 v[84:87], v[176:179], v[152:155], v[84:87]
	v_mfma_f32_16x16x32_bf16 v[80:83], v[184:187], v[152:155], v[80:83]
	v_mfma_f32_16x16x32_bf16 v[76:79], v[176:179], v[160:163], v[76:79]
	v_mfma_f32_16x16x32_bf16 v[72:75], v[184:187], v[160:163], v[72:75]
	v_mfma_f32_16x16x32_bf16 v[68:71], v[176:179], v[168:171], v[68:71]
	v_mfma_f32_16x16x32_bf16 v[64:67], v[184:187], v[168:171], v[64:67]
	v_mfma_f32_16x16x32_bf16 v[92:95], v[180:183], v[148:151], v[92:95]
	v_mfma_f32_16x16x32_bf16 v[88:91], v[188:191], v[148:151], v[88:91]
	v_mfma_f32_16x16x32_bf16 v[84:87], v[180:183], v[156:159], v[84:87]
	v_mfma_f32_16x16x32_bf16 v[80:83], v[188:191], v[156:159], v[80:83]
	v_mfma_f32_16x16x32_bf16 v[76:79], v[180:183], v[164:167], v[76:79]
	v_mfma_f32_16x16x32_bf16 v[72:75], v[188:191], v[164:167], v[72:75]
	v_mfma_f32_16x16x32_bf16 v[68:71], v[180:183], v[172:175], v[68:71]
	v_mfma_f32_16x16x32_bf16 v[64:67], v[188:191], v[172:175], v[64:67]
	s_barrier
	ds_read_b128 v[144:147], v222 offset:0
	ds_read_b128 v[148:151], v222 offset:0x400
	ds_read_b128 v[152:155], v222 offset:0x800
	ds_read_b128 v[156:159], v222 offset:0xc00
	ds_read_b128 v[160:163], v222 offset:0x1000
	ds_read_b128 v[164:167], v222 offset:0x1400
	ds_read_b128 v[168:171], v222 offset:0x1800
	s_mov_b64 s[84:85], 0x100
	s_mov_b32 m0, s3
	ds_read_b128 v[172:175], v222 offset:0x1c00
	s_mov_b64 s[84:85], 0x40100
	s_add_u32 s94, s76, 0x100
	s_addc_u32 s95, s77, 0
	global_load_lds_dwordx4 v210, s[94:95]
	s_mov_b32 m0, s31
	s_add_u32 s94, s76, 0x40100
	s_addc_u32 s95, s77, 0
	global_load_lds_dwordx4 v210, s[94:95]
	s_barrier
	s_waitcnt lgkmcnt(0)
	v_mfma_f32_16x16x32_bf16 v[60:63], v[128:131], v[144:147], v[60:63]
	v_mfma_f32_16x16x32_bf16 v[56:59], v[136:139], v[144:147], v[56:59]
	v_mfma_f32_16x16x32_bf16 v[52:55], v[128:131], v[152:155], v[52:55]
	v_mfma_f32_16x16x32_bf16 v[48:51], v[136:139], v[152:155], v[48:51]
	v_mfma_f32_16x16x32_bf16 v[44:47], v[128:131], v[160:163], v[44:47]
	v_mfma_f32_16x16x32_bf16 v[40:43], v[136:139], v[160:163], v[40:43]
	v_mfma_f32_16x16x32_bf16 v[36:39], v[128:131], v[168:171], v[36:39]
	v_mfma_f32_16x16x32_bf16 v[32:35], v[136:139], v[168:171], v[32:35]
	v_mfma_f32_16x16x32_bf16 v[60:63], v[132:135], v[148:151], v[60:63]
	v_mfma_f32_16x16x32_bf16 v[56:59], v[140:143], v[148:151], v[56:59]
	v_mfma_f32_16x16x32_bf16 v[52:55], v[132:135], v[156:159], v[52:55]
	v_mfma_f32_16x16x32_bf16 v[48:51], v[140:143], v[156:159], v[48:51]
	v_mfma_f32_16x16x32_bf16 v[44:47], v[132:135], v[164:167], v[44:47]
	v_mfma_f32_16x16x32_bf16 v[40:43], v[140:143], v[164:167], v[40:43]
	v_mfma_f32_16x16x32_bf16 v[36:39], v[132:135], v[172:175], v[36:39]
	v_mfma_f32_16x16x32_bf16 v[32:35], v[140:143], v[172:175], v[32:35]
	s_barrier
	s_mov_b64 s[84:85], 0x30180100
	s_mov_b32 m0, s50
	s_mov_b64 s[84:85], 0x301c0100
	s_add_u32 s94, s74, 0x30180100
	s_addc_u32 s95, s75, 0
	global_load_lds_dwordx4 v210, s[94:95]
	s_mov_b32 m0, s51
	s_add_u32 s94, s74, 0x301c0100
	s_addc_u32 s95, s75, 0
	global_load_lds_dwordx4 v210, s[94:95]
	s_waitcnt vmcnt(6)
	s_barrier
; #define WAIT_V(n) asm volatile("s_waitcnt vmcnt(%0)" ::"n"(n) : "memory")
; #define SCHED() __builtin_amdgcn_sched_barrier(0)
; #define LGKM(n) asm volatile("s_waitcnt lgkmcnt(%0)" ::"n"(n) : "memory")
; #define STAGE_A(b, h, kt) STAGE_AX(Ag, b, h, kt)
; #define STAGE_B(b, h, kt) STAGE_BX(Bg, b, h, kt)
; #define LDA(b, h) do { const unsigned pa_ = lds0 + SLOTA(b, h) + wr * 8192 + laneoff; _Pragma("unroll") for (int m = 0; m < 4; ++m)   \
;       _Pragma("unroll") for (int k = 0; k < 2; ++k) DSR(At[m][k], pa_, m * 2048 + k * 1024); } while (0)
; #define LDB(dst, b, h) do { const unsigned pb_ = lds0 + SLOTB(b, h) + wc * 4096 + laneoff; _Pragma("unroll") for (int n = 0; n < 2; ++n) \
;       _Pragma("unroll") for (int k = 0; k < 2; ++k) DSR(dst[n][k], pb_, n * 2048 + k * 1024); } while (0)
; #define BAR __builtin_amdgcn_s_barrier()
; #define LGKM(n) asm volatile("s_waitcnt lgkmcnt(%0)" ::"n"(n) : "memory")
; template <int EPI, bool SWP> ...
;     ...
;     WAIT_V(6); BAR; SCHED(); MMA(1, 1, B1); BAR; SCHED();
;     LDB(B0, 1, 0); LDA(1, 0); STAGE_A(0, 1, t + 2);
;     LGKM(8); BAR; LGKM(0); SCHED(); MMA(0, 0, B0); BAR; SCHED();
;     LDB(B1, 1, 1); STAGE_B(1, 0, t + 3);
;     BAR; LGKM(0); SCHED(); MMA(0, 1, B1); BAR; SCHED();
;     LDA(1, 1); STAGE_A(1, 0, t + 3);
;     BAR; LGKM(0); SCHED(); MMA(1, 0, B0); BAR; SCHED();
	v_mfma_f32_16x16x32_bf16 v[28:31], v[176:179], v[144:147], v[28:31]
	v_mfma_f32_16x16x32_bf16 v[24:27], v[184:187], v[144:147], v[24:27]
	v_mfma_f32_16x16x32_bf16 v[20:23], v[176:179], v[152:155], v[20:23]
	v_mfma_f32_16x16x32_bf16 v[16:19], v[184:187], v[152:155], v[16:19]
	v_mfma_f32_16x16x32_bf16 v[12:15], v[176:179], v[160:163], v[12:15]
	v_mfma_f32_16x16x32_bf16 v[8:11], v[184:187], v[160:163], v[8:11]
	v_mfma_f32_16x16x32_bf16 v[4:7], v[176:179], v[168:171], v[4:7]
	v_mfma_f32_16x16x32_bf16 v[0:3], v[184:187], v[168:171], v[0:3]
	v_mfma_f32_16x16x32_bf16 v[28:31], v[180:183], v[148:151], v[28:31]
	v_mfma_f32_16x16x32_bf16 v[24:27], v[188:191], v[148:151], v[24:27]
	v_mfma_f32_16x16x32_bf16 v[20:23], v[180:183], v[156:159], v[20:23]
	v_mfma_f32_16x16x32_bf16 v[16:19], v[188:191], v[156:159], v[16:19]
	v_mfma_f32_16x16x32_bf16 v[12:15], v[180:183], v[164:167], v[12:15]
	v_mfma_f32_16x16x32_bf16 v[8:11], v[188:191], v[164:167], v[8:11]
	v_mfma_f32_16x16x32_bf16 v[4:7], v[180:183], v[172:175], v[4:7]
	v_mfma_f32_16x16x32_bf16 v[0:3], v[188:191], v[172:175], v[0:3]
	s_barrier
	ds_read_b128 v[128:131], v223 offset:0
	ds_read_b128 v[132:135], v223 offset:0x400
	ds_read_b128 v[136:139], v223 offset:0x800
	ds_read_b128 v[140:143], v223 offset:0xc00
	ds_read_b128 v[144:147], v224 offset:0
	ds_read_b128 v[148:151], v224 offset:0x400
	ds_read_b128 v[152:155], v224 offset:0x800
	ds_read_b128 v[156:159], v224 offset:0xc00
	ds_read_b128 v[160:163], v224 offset:0x1000
	ds_read_b128 v[164:167], v224 offset:0x1400
	ds_read_b128 v[168:171], v224 offset:0x1800
	s_mov_b64 s[84:85], 0x80100
	s_mov_b32 m0, s64
	ds_read_b128 v[172:175], v224 offset:0x1c00
	s_mov_b64 s[84:85], 0xc0100
	s_add_u32 s94, s76, 0x80100
	s_addc_u32 s95, s77, 0
	global_load_lds_dwordx4 v210, s[94:95]
	s_mov_b32 m0, s65
	s_add_u32 s94, s76, 0xc0100
	s_addc_u32 s95, s77, 0
	global_load_lds_dwordx4 v210, s[94:95]
	s_waitcnt lgkmcnt(8)
	s_barrier
	s_waitcnt lgkmcnt(0)
	v_mfma_f32_16x16x32_bf16 v[124:127], v[128:131], v[144:147], v[124:127]
	v_mfma_f32_16x16x32_bf16 v[120:123], v[136:139], v[144:147], v[120:123]
	v_mfma_f32_16x16x32_bf16 v[116:119], v[128:131], v[152:155], v[116:119]
	v_mfma_f32_16x16x32_bf16 v[112:115], v[136:139], v[152:155], v[112:115]
	v_mfma_f32_16x16x32_bf16 v[108:111], v[128:131], v[160:163], v[108:111]
	v_mfma_f32_16x16x32_bf16 v[104:107], v[136:139], v[160:163], v[104:107]
	v_mfma_f32_16x16x32_bf16 v[100:103], v[128:131], v[168:171], v[100:103]
	v_mfma_f32_16x16x32_bf16 v[96:99], v[136:139], v[168:171], v[96:99]
	v_mfma_f32_16x16x32_bf16 v[124:127], v[132:135], v[148:151], v[124:127]
	v_mfma_f32_16x16x32_bf16 v[120:123], v[140:143], v[148:151], v[120:123]
	v_mfma_f32_16x16x32_bf16 v[116:119], v[132:135], v[156:159], v[116:119]
	v_mfma_f32_16x16x32_bf16 v[112:115], v[140:143], v[156:159], v[112:115]
	v_mfma_f32_16x16x32_bf16 v[108:111], v[132:135], v[164:167], v[108:111]
	v_mfma_f32_16x16x32_bf16 v[104:107], v[140:143], v[164:167], v[104:107]
	v_mfma_f32_16x16x32_bf16 v[100:103], v[132:135], v[172:175], v[100:103]
	v_mfma_f32_16x16x32_bf16 v[96:99], v[140:143], v[172:175], v[96:99]
	s_barrier
	ds_read_b128 v[176:179], v225 offset:0
	ds_read_b128 v[180:183], v225 offset:0x400
	ds_read_b128 v[184:187], v225 offset:0x800
	s_mov_b64 s[84:85], 0x30100180
	s_add_i32 s83, s3, 0x18000
	ds_read_b128 v[188:191], v225 offset:0xc00
	s_mov_b32 m0, s83
	s_mov_b64 s[84:85], 0x30140180
	s_add_u32 s94, s74, 0x30100180
	s_addc_u32 s95, s75, 0
	global_load_lds_dwordx4 v210, s[94:95]
	s_mov_b32 m0, s66
	s_add_u32 s94, s74, 0x30140180
	s_addc_u32 s95, s75, 0
	global_load_lds_dwordx4 v210, s[94:95]
	s_barrier
	s_waitcnt lgkmcnt(0)
	v_mfma_f32_16x16x32_bf16 v[92:95], v[176:179], v[144:147], v[92:95]
	v_mfma_f32_16x16x32_bf16 v[88:91], v[184:187], v[144:147], v[88:91]
	v_mfma_f32_16x16x32_bf16 v[84:87], v[176:179], v[152:155], v[84:87]
	v_mfma_f32_16x16x32_bf16 v[80:83], v[184:187], v[152:155], v[80:83]
	v_mfma_f32_16x16x32_bf16 v[76:79], v[176:179], v[160:163], v[76:79]
	v_mfma_f32_16x16x32_bf16 v[72:75], v[184:187], v[160:163], v[72:75]
	v_mfma_f32_16x16x32_bf16 v[68:71], v[176:179], v[168:171], v[68:71]
	v_mfma_f32_16x16x32_bf16 v[64:67], v[184:187], v[168:171], v[64:67]
	v_mfma_f32_16x16x32_bf16 v[92:95], v[180:183], v[148:151], v[92:95]
	v_mfma_f32_16x16x32_bf16 v[88:91], v[188:191], v[148:151], v[88:91]
	v_mfma_f32_16x16x32_bf16 v[84:87], v[180:183], v[156:159], v[84:87]
	v_mfma_f32_16x16x32_bf16 v[80:83], v[188:191], v[156:159], v[80:83]
	v_mfma_f32_16x16x32_bf16 v[76:79], v[180:183], v[164:167], v[76:79]
	v_mfma_f32_16x16x32_bf16 v[72:75], v[188:191], v[164:167], v[72:75]
	v_mfma_f32_16x16x32_bf16 v[68:71], v[180:183], v[172:175], v[68:71]
	v_mfma_f32_16x16x32_bf16 v[64:67], v[188:191], v[172:175], v[64:67]
	s_barrier
	ds_read_b128 v[144:147], v226 offset:0
	ds_read_b128 v[148:151], v226 offset:0x400
	ds_read_b128 v[152:155], v226 offset:0x800
	ds_read_b128 v[156:159], v226 offset:0xc00
	ds_read_b128 v[160:163], v226 offset:0x1000
	ds_read_b128 v[164:167], v226 offset:0x1400
	s_mov_b64 s[84:85], 0x180
	ds_read_b128 v[168:171], v226 offset:0x1800
	s_add_i32 s84, s3, 0x8000
	ds_read_b128 v[172:175], v226 offset:0x1c00
	s_mov_b32 m0, s84
	s_mov_b64 s[86:87], 0x40180
	s_add_u32 s94, s76, 0x180
	s_addc_u32 s95, s77, 0
	global_load_lds_dwordx4 v210, s[94:95]
	v_lshl_add_u64 v[192:193], v[192:193], 0, s[86:87]
	s_mov_b32 m0, s67
	s_add_u32 s94, s76, 0x40180
	s_addc_u32 s95, s77, 0
	global_load_lds_dwordx4 v210, s[94:95]
	s_barrier
; #define WAIT_V(n) asm volatile("s_waitcnt vmcnt(%0)" ::"n"(n) : "memory")
; #define SCHED() __builtin_amdgcn_sched_barrier(0)
; #define LGKM(n) asm volatile("s_waitcnt lgkmcnt(%0)" ::"n"(n) : "memory")
; #define STAGE_A(b, h, kt) STAGE_AX(Ag, b, h, kt)
; #define STAGE_B(b, h, kt) STAGE_BX(Bg, b, h, kt)
; #define LDA(b, h) do { const unsigned pa_ = lds0 + SLOTA(b, h) + wr * 8192 + laneoff; _Pragma("unroll") for (int m = 0; m < 4; ++m)   \
;       _Pragma("unroll") for (int k = 0; k < 2; ++k) DSR(At[m][k], pa_, m * 2048 + k * 1024); } while (0)
; #define LDB(dst, b, h) do { const unsigned pb_ = lds0 + SLOTB(b, h) + wc * 4096 + laneoff; _Pragma("unroll") for (int n = 0; n < 2; ++n) \
;       _Pragma("unroll") for (int k = 0; k < 2; ++k) DSR(dst[n][k], pb_, n * 2048 + k * 1024); } while (0)
; #define BAR __builtin_amdgcn_s_barrier()
; #define LGKM(n) asm volatile("s_waitcnt lgkmcnt(%0)" ::"n"(n) : "memory")
; template <int EPI, bool SWP> ...
;     ...
;     STAGE_B(1, 1, t + 3);
;     WAIT_V(6); BAR; SCHED(); MMA(1, 1, B1); BAR; SCHED();
;   }
;   { LDB(B0, 0, 0); LDA(0, 0); STAGE_A(1, 1, nt - 1);
;     BAR; LGKM(0); SCHED(); MMA(0, 0, B0); BAR; SCHED();
;     LDB(B1, 0, 1); BAR; LGKM(0); SCHED(); MMA(0, 1, B1); BAR; SCHED();
;     LDA(0, 1); WAIT_V(4); BAR; LGKM(0); SCHED(); MMA(1, 0, B0); MMA(1, 1, B1); BAR; SCHED(); }
	s_waitcnt lgkmcnt(0)
	v_mfma_f32_16x16x32_bf16 v[60:63], v[128:131], v[144:147], v[60:63]
	v_mfma_f32_16x16x32_bf16 v[56:59], v[136:139], v[144:147], v[56:59]
	v_mfma_f32_16x16x32_bf16 v[52:55], v[128:131], v[152:155], v[52:55]
	v_mfma_f32_16x16x32_bf16 v[48:51], v[136:139], v[152:155], v[48:51]
	v_mfma_f32_16x16x32_bf16 v[44:47], v[128:131], v[160:163], v[44:47]
	v_mfma_f32_16x16x32_bf16 v[40:43], v[136:139], v[160:163], v[40:43]
	v_mfma_f32_16x16x32_bf16 v[36:39], v[128:131], v[168:171], v[36:39]
	v_mfma_f32_16x16x32_bf16 v[32:35], v[136:139], v[168:171], v[32:35]
	v_mfma_f32_16x16x32_bf16 v[60:63], v[132:135], v[148:151], v[60:63]
	v_mfma_f32_16x16x32_bf16 v[56:59], v[140:143], v[148:151], v[56:59]
	v_mfma_f32_16x16x32_bf16 v[52:55], v[132:135], v[156:159], v[52:55]
	v_mfma_f32_16x16x32_bf16 v[48:51], v[140:143], v[156:159], v[48:51]
	v_mfma_f32_16x16x32_bf16 v[44:47], v[132:135], v[164:167], v[44:47]
	v_mfma_f32_16x16x32_bf16 v[40:43], v[140:143], v[164:167], v[40:43]
	v_mfma_f32_16x16x32_bf16 v[36:39], v[132:135], v[172:175], v[36:39]
	v_mfma_f32_16x16x32_bf16 v[32:35], v[140:143], v[172:175], v[32:35]
	s_barrier
	s_mov_b64 s[86:87], 0x30180180
	s_add_i32 s85, s3, 0x1c000
	s_mov_b32 m0, s85
	s_mov_b64 s[86:87], 0x301c0180
	s_add_u32 s94, s74, 0x30180180
	s_addc_u32 s95, s75, 0
	global_load_lds_dwordx4 v210, s[94:95]
	s_mov_b32 m0, s78
	s_add_u32 s94, s74, 0x301c0180
	s_addc_u32 s95, s75, 0
	global_load_lds_dwordx4 v210, s[94:95]
	s_waitcnt vmcnt(6)
	s_barrier
	v_mfma_f32_16x16x32_bf16 v[28:31], v[176:179], v[144:147], v[28:31]
	v_mfma_f32_16x16x32_bf16 v[24:27], v[184:187], v[144:147], v[24:27]
	v_mfma_f32_16x16x32_bf16 v[20:23], v[176:179], v[152:155], v[20:23]
	v_mfma_f32_16x16x32_bf16 v[16:19], v[184:187], v[152:155], v[16:19]
	v_mfma_f32_16x16x32_bf16 v[12:15], v[176:179], v[160:163], v[12:15]
	v_mfma_f32_16x16x32_bf16 v[8:11], v[184:187], v[160:163], v[8:11]
	v_mfma_f32_16x16x32_bf16 v[4:7], v[176:179], v[168:171], v[4:7]
	v_mfma_f32_16x16x32_bf16 v[0:3], v[184:187], v[168:171], v[0:3]
	v_mfma_f32_16x16x32_bf16 v[28:31], v[180:183], v[148:151], v[28:31]
	v_mfma_f32_16x16x32_bf16 v[24:27], v[188:191], v[148:151], v[24:27]
	v_mfma_f32_16x16x32_bf16 v[20:23], v[180:183], v[156:159], v[20:23]
	v_mfma_f32_16x16x32_bf16 v[16:19], v[188:191], v[156:159], v[16:19]
	v_mfma_f32_16x16x32_bf16 v[12:15], v[180:183], v[164:167], v[12:15]
	v_mfma_f32_16x16x32_bf16 v[8:11], v[188:191], v[164:167], v[8:11]
	v_mfma_f32_16x16x32_bf16 v[4:7], v[180:183], v[172:175], v[4:7]
	v_mfma_f32_16x16x32_bf16 v[0:3], v[188:191], v[172:175], v[0:3]
	s_add_i32 s15, s15, 2
	s_add_u32 s74, s74, 0x100
	s_addc_u32 s75, s75, 0
	s_add_u32 s76, s76, 0x100
	s_addc_u32 s77, s77, 0
	s_cmp_gt_u32 s15, 27
	s_barrier
	s_cbranch_scc0 .LBB0_81
	ds_read_b128 v[136:139], v219 offset:0
	ds_read_b128 v[140:143], v219 offset:0x400
	ds_read_b128 v[144:147], v219 offset:0x800
	ds_read_b128 v[148:151], v219 offset:0xc00
	ds_read_b128 v[128:131], v220 offset:0
	ds_read_b128 v[132:135], v220 offset:0x400
	ds_read_b128 v[152:155], v220 offset:0x800
	ds_read_b128 v[156:159], v220 offset:0xc00
	ds_read_b128 v[160:163], v220 offset:0x1000
	ds_read_b128 v[164:167], v220 offset:0x1400
	v_lshl_add_u64 v[176:177], s[72:73], 0, v[208:209]
	ds_read_b128 v[168:171], v220 offset:0x1800
	s_mov_b64 s[72:73], 0x80f80
	s_mov_b32 m0, s79
	ds_read_b128 v[172:175], v220 offset:0x1c00
	v_lshl_add_u64 v[178:179], v[176:177], 0, s[72:73]
	s_mov_b64 s[72:73], 0xc0f80
	global_load_lds_dwordx4 v[178:179], off
	v_lshl_add_u64 v[176:177], v[176:177], 0, s[72:73]
	s_mov_b32 m0, s80
	s_ashr_i32 s15, s14, 31
	global_load_lds_dwordx4 v[176:177], off
	s_lshl_b64 s[72:73], s[14:15], 20
	s_add_u32 s72, s56, s72
	s_addc_u32 s73, s57, s73
	s_ashr_i32 s61, s60, 31
	s_barrier
	s_waitcnt lgkmcnt(0)
	s_lshl_b64 s[74:75], s[60:61], 20
	s_add_u32 s74, s10, s74
	s_addc_u32 s75, s11, s75
	v_mfma_f32_16x16x32_bf16 v[124:127], v[136:139], v[128:131], v[124:127]
	v_mfma_f32_16x16x32_bf16 v[120:123], v[144:147], v[128:131], v[120:123]
	v_mfma_f32_16x16x32_bf16 v[116:119], v[136:139], v[152:155], v[116:119]
	v_mfma_f32_16x16x32_bf16 v[112:115], v[144:147], v[152:155], v[112:115]
	v_mfma_f32_16x16x32_bf16 v[108:111], v[136:139], v[160:163], v[108:111]
	v_mfma_f32_16x16x32_bf16 v[104:107], v[144:147], v[160:163], v[104:107]
	v_mfma_f32_16x16x32_bf16 v[100:103], v[136:139], v[168:171], v[100:103]
	v_mfma_f32_16x16x32_bf16 v[96:99], v[144:147], v[168:171], v[96:99]
	v_mfma_f32_16x16x32_bf16 v[124:127], v[140:143], v[132:135], v[124:127]
	v_mfma_f32_16x16x32_bf16 v[120:123], v[148:151], v[132:135], v[120:123]
	v_mfma_f32_16x16x32_bf16 v[116:119], v[140:143], v[156:159], v[116:119]
	v_mfma_f32_16x16x32_bf16 v[112:115], v[148:151], v[156:159], v[112:115]
	v_mfma_f32_16x16x32_bf16 v[176:179], v[140:143], v[164:167], v[108:111]
	v_mfma_f32_16x16x32_bf16 v[180:183], v[148:151], v[164:167], v[104:107]
	v_mfma_f32_16x16x32_bf16 v[100:103], v[140:143], v[172:175], v[100:103]
	v_mfma_f32_16x16x32_bf16 v[96:99], v[148:151], v[172:175], v[96:99]
	s_barrier
	ds_read_b128 v[104:107], v221 offset:0
	ds_read_b128 v[108:111], v221 offset:0x400
	ds_read_b128 v[184:187], v221 offset:0x800
	ds_read_b128 v[188:191], v221 offset:0xc00
	s_barrier
; #define WAIT_V(n) asm volatile("s_waitcnt vmcnt(%0)" ::"n"(n) : "memory")
; #define SCHED() __builtin_amdgcn_sched_barrier(0)
; #define LGKM(n) asm volatile("s_waitcnt lgkmcnt(%0)" ::"n"(n) : "memory")
; #define LDA(b, h) do { const unsigned pa_ = lds0 + SLOTA(b, h) + wr * 8192 + laneoff; _Pragma("unroll") for (int m = 0; m < 4; ++m)   \
;       _Pragma("unroll") for (int k = 0; k < 2; ++k) DSR(At[m][k], pa_, m * 2048 + k * 1024); } while (0)
; #define LDB(dst, b, h) do { const unsigned pb_ = lds0 + SLOTB(b, h) + wc * 4096 + laneoff; _Pragma("unroll") for (int n = 0; n < 2; ++n) \
;       _Pragma("unroll") for (int k = 0; k < 2; ++k) DSR(dst[n][k], pb_, n * 2048 + k * 1024); } while (0)
; #define BAR __builtin_amdgcn_s_barrier()
; #define LGKM(n) asm volatile("s_waitcnt lgkmcnt(%0)" ::"n"(n) : "memory")
; template <int EPI, bool SWP> ...
;     ...
;     LDA(0, 1); WAIT_V(4); BAR; LGKM(0); SCHED(); MMA(1, 0, B0); MMA(1, 1, B1); BAR; SCHED(); }
;   { LDB(B0, 1, 0); LDA(1, 0); WAIT_V(2); BAR; LGKM(0); SCHED(); MMA(0, 0, B0); BAR; SCHED();
	s_waitcnt lgkmcnt(0)
	v_mfma_f32_16x16x32_bf16 v[92:95], v[104:107], v[128:131], v[92:95]
	v_mfma_f32_16x16x32_bf16 v[88:91], v[184:187], v[128:131], v[88:91]
	v_mfma_f32_16x16x32_bf16 v[84:87], v[104:107], v[152:155], v[84:87]
	v_mfma_f32_16x16x32_bf16 v[80:83], v[184:187], v[152:155], v[80:83]
	v_mfma_f32_16x16x32_bf16 v[76:79], v[104:107], v[160:163], v[76:79]
	v_mfma_f32_16x16x32_bf16 v[72:75], v[184:187], v[160:163], v[72:75]
	v_mfma_f32_16x16x32_bf16 v[68:71], v[104:107], v[168:171], v[68:71]
	v_mfma_f32_16x16x32_bf16 v[64:67], v[184:187], v[168:171], v[64:67]
	v_mfma_f32_16x16x32_bf16 v[192:195], v[108:111], v[132:135], v[92:95]
	v_mfma_f32_16x16x32_bf16 v[196:199], v[188:191], v[132:135], v[88:91]
	v_mfma_f32_16x16x32_bf16 v[84:87], v[108:111], v[156:159], v[84:87]
	v_mfma_f32_16x16x32_bf16 v[80:83], v[188:191], v[156:159], v[80:83]
	v_mfma_f32_16x16x32_bf16 v[200:203], v[108:111], v[164:167], v[76:79]
	v_mfma_f32_16x16x32_bf16 v[204:207], v[188:191], v[164:167], v[72:75]
	v_mfma_f32_16x16x32_bf16 v[68:71], v[108:111], v[172:175], v[68:71]
	v_mfma_f32_16x16x32_bf16 v[64:67], v[188:191], v[172:175], v[64:67]
	s_barrier
	ds_read_b128 v[72:75], v222 offset:0
	ds_read_b128 v[76:79], v222 offset:0x400
	ds_read_b128 v[88:91], v222 offset:0x800
	ds_read_b128 v[92:95], v222 offset:0xc00
	ds_read_b128 v[152:155], v222 offset:0x1000
	ds_read_b128 v[156:159], v222 offset:0x1400
	ds_read_b128 v[160:163], v222 offset:0x1800
	ds_read_b128 v[164:167], v222 offset:0x1c00
	s_waitcnt vmcnt(4)
	s_barrier
	s_waitcnt lgkmcnt(0)
	v_mfma_f32_16x16x32_bf16 v[60:63], v[136:139], v[72:75], v[60:63]
	v_mfma_f32_16x16x32_bf16 v[56:59], v[144:147], v[72:75], v[56:59]
	v_mfma_f32_16x16x32_bf16 v[52:55], v[136:139], v[88:91], v[52:55]
	v_mfma_f32_16x16x32_bf16 v[48:51], v[144:147], v[88:91], v[48:51]
	v_mfma_f32_16x16x32_bf16 v[44:47], v[136:139], v[152:155], v[44:47]
	v_mfma_f32_16x16x32_bf16 v[40:43], v[144:147], v[152:155], v[40:43]
	v_mfma_f32_16x16x32_bf16 v[36:39], v[136:139], v[160:163], v[36:39]
	v_mfma_f32_16x16x32_bf16 v[32:35], v[144:147], v[160:163], v[32:35]
	v_mfma_f32_16x16x32_bf16 v[60:63], v[140:143], v[76:79], v[60:63]
	v_mfma_f32_16x16x32_bf16 v[56:59], v[148:151], v[76:79], v[56:59]
	v_mfma_f32_16x16x32_bf16 v[52:55], v[140:143], v[92:95], v[52:55]
	v_mfma_f32_16x16x32_bf16 v[48:51], v[148:151], v[92:95], v[48:51]
	v_mfma_f32_16x16x32_bf16 v[128:131], v[140:143], v[156:159], v[44:47]
	v_mfma_f32_16x16x32_bf16 v[132:135], v[148:151], v[156:159], v[40:43]
	v_mfma_f32_16x16x32_bf16 v[36:39], v[140:143], v[164:167], v[36:39]
	v_mfma_f32_16x16x32_bf16 v[32:35], v[148:151], v[164:167], v[32:35]
	v_mfma_f32_16x16x32_bf16 v[28:31], v[104:107], v[72:75], v[28:31]
	v_mfma_f32_16x16x32_bf16 v[24:27], v[184:187], v[72:75], v[24:27]
	v_mfma_f32_16x16x32_bf16 v[20:23], v[104:107], v[88:91], v[20:23]
	v_mfma_f32_16x16x32_bf16 v[16:19], v[184:187], v[88:91], v[16:19]
	v_mfma_f32_16x16x32_bf16 v[12:15], v[104:107], v[152:155], v[12:15]
	v_mfma_f32_16x16x32_bf16 v[8:11], v[184:187], v[152:155], v[8:11]
	v_mfma_f32_16x16x32_bf16 v[4:7], v[104:107], v[160:163], v[4:7]
	v_mfma_f32_16x16x32_bf16 v[0:3], v[184:187], v[160:163], v[0:3]
	v_mfma_f32_16x16x32_bf16 v[136:139], v[108:111], v[76:79], v[28:31]
	v_mfma_f32_16x16x32_bf16 v[140:143], v[188:191], v[76:79], v[24:27]
	v_mfma_f32_16x16x32_bf16 v[20:23], v[108:111], v[92:95], v[20:23]
	v_mfma_f32_16x16x32_bf16 v[16:19], v[188:191], v[92:95], v[16:19]
	v_mfma_f32_16x16x32_bf16 v[144:147], v[108:111], v[156:159], v[12:15]
	v_mfma_f32_16x16x32_bf16 v[148:151], v[188:191], v[156:159], v[8:11]
	v_mfma_f32_16x16x32_bf16 v[4:7], v[108:111], v[164:167], v[4:7]
	v_mfma_f32_16x16x32_bf16 v[0:3], v[188:191], v[164:167], v[0:3]
	s_barrier
	ds_read_b128 v[8:11], v223 offset:0
	ds_read_b128 v[12:15], v223 offset:0x400
	ds_read_b128 v[152:155], v223 offset:0x800
	ds_read_b128 v[156:159], v223 offset:0xc00
	ds_read_b128 v[24:27], v224 offset:0
	ds_read_b128 v[28:31], v224 offset:0x400
	ds_read_b128 v[40:43], v224 offset:0x800
	ds_read_b128 v[44:47], v224 offset:0xc00
	ds_read_b128 v[184:187], v224 offset:0x1000
	ds_read_b128 v[188:191], v224 offset:0x1400
	ds_read_b128 v[212:215], v224 offset:0x1800
	ds_read_b128 v[236:239], v224 offset:0x1c00
	s_waitcnt vmcnt(2)
	s_barrier
; #define WAIT_V(n) asm volatile("s_waitcnt vmcnt(%0)" ::"n"(n) : "memory")
; #define SCHED() __builtin_amdgcn_sched_barrier(0)
; #define LGKM(n) asm volatile("s_waitcnt lgkmcnt(%0)" ::"n"(n) : "memory")
; #define STAGE_AX(AG, b, h, kt) do { _Pragma("unroll") for (int i = 0; i < 2; ++i)                                    \
;       __builtin_amdgcn_global_load_lds((const unsigned*)(((AG) + ((size_t)(kt) * (BK * 2) + (size_t)((h) * 2 + i) * 128 * lda)) + aoff), \
;                                        (unsigned*)(shm + SLOTA(b, h) + wid * 1024 + i * 8192), 16, 0, 0); } while (0)
; #define STAGE_BX(BG, b, h, kt) do { _Pragma("unroll") for (int i = 0; i < 2; ++i)                                    \
;       __builtin_amdgcn_global_load_lds((const unsigned*)(((BG) + ((size_t)(kt) * (BK * 2) + (size_t)((h) * 2 + i) * 128 * K)) + boff),   \
;                                        (unsigned*)(shm + SLOTB(b, h) + wid * 1024 + i * 8192), 16, 0, 0); } while (0)
; #define LDA(b, h) do { const unsigned pa_ = lds0 + SLOTA(b, h) + wr * 8192 + laneoff; _Pragma("unroll") for (int m = 0; m < 4; ++m)   \
;       _Pragma("unroll") for (int k = 0; k < 2; ++k) DSR(At[m][k], pa_, m * 2048 + k * 1024); } while (0)
; #define LDB(dst, b, h) do { const unsigned pb_ = lds0 + SLOTB(b, h) + wc * 4096 + laneoff; _Pragma("unroll") for (int n = 0; n < 2; ++n) \
;       _Pragma("unroll") for (int k = 0; k < 2; ++k) DSR(dst[n][k], pb_, n * 2048 + k * 1024); } while (0)
; #define BAR __builtin_amdgcn_s_barrier()
; #define LGKM(n) asm volatile("s_waitcnt lgkmcnt(%0)" ::"n"(n) : "memory")
; template <int EPI, bool SWP> ...
;     ...
;   { LDB(B0, 1, 0); LDA(1, 0); WAIT_V(2); BAR; LGKM(0); SCHED(); MMA(0, 0, B0); BAR; SCHED();
;     LDB(B1, 1, 1); WAIT_V(0); BAR; LGKM(0); SCHED(); MMA(0, 1, B1); BAR; SCHED();
;     LDA(1, 1);
;     if (has_next) { STAGE_BX(Bg_n, 0, 0, 0); STAGE_AX(Ag_n, 0, 0, 0); STAGE_BX(Bg_n, 0, 1, 0); STAGE_AX(Ag_n, 0, 1, 0); }
;     BAR; LGKM(0); SCHED(); MMA(1, 0, B0); MMA(1, 1, B1); BAR; SCHED(); }
;   if (wr == 0) BAR;
;   if (has_next) {
;     STAGE_BX(Bg_n, 1, 0, 1); STAGE_AX(Ag_n, 1, 0, 1); STAGE_BX(Bg_n, 1, 1, 1);
;     if (e.nss > 0 && tid < 256) s_rstd_n[tid] = rsqrtf(ss_next * (1.f / DM) + 1e-6f);
	s_waitcnt lgkmcnt(0)
	v_mfma_f32_16x16x32_bf16 v[72:75], v[8:11], v[24:27], v[124:127]
	v_mfma_f32_16x16x32_bf16 v[124:127], v[12:15], v[28:31], v[72:75]
	v_mfma_f32_16x16x32_bf16 v[72:75], v[152:155], v[24:27], v[120:123]
	v_mfma_f32_16x16x32_bf16 v[120:123], v[156:159], v[28:31], v[72:75]
	v_mfma_f32_16x16x32_bf16 v[72:75], v[8:11], v[40:43], v[116:119]
	v_mfma_f32_16x16x32_bf16 v[108:111], v[12:15], v[44:47], v[72:75]
	v_mfma_f32_16x16x32_bf16 v[72:75], v[152:155], v[40:43], v[112:115]
	v_mfma_f32_16x16x32_bf16 v[104:107], v[156:159], v[44:47], v[72:75]
	v_mfma_f32_16x16x32_bf16 v[72:75], v[8:11], v[184:187], v[176:179]
	v_mfma_f32_16x16x32_bf16 v[92:95], v[12:15], v[188:191], v[72:75]
	v_mfma_f32_16x16x32_bf16 v[72:75], v[152:155], v[184:187], v[180:183]
	v_mfma_f32_16x16x32_bf16 v[88:91], v[156:159], v[188:191], v[72:75]
	v_mfma_f32_16x16x32_bf16 v[72:75], v[8:11], v[212:215], v[100:103]
	v_mfma_f32_16x16x32_bf16 v[76:79], v[12:15], v[236:239], v[72:75]
	v_mfma_f32_16x16x32_bf16 v[72:75], v[152:155], v[212:215], v[96:99]
	v_mfma_f32_16x16x32_bf16 v[72:75], v[156:159], v[236:239], v[72:75]
	s_barrier
	ds_read_b128 v[160:163], v225 offset:0
	ds_read_b128 v[164:167], v225 offset:0x400
	ds_read_b128 v[168:171], v225 offset:0x800
	ds_read_b128 v[172:175], v225 offset:0xc00
	s_waitcnt vmcnt(0)
	s_barrier
	s_waitcnt lgkmcnt(0)
	v_mfma_f32_16x16x32_bf16 v[96:99], v[160:163], v[24:27], v[192:195]
	v_mfma_f32_16x16x32_bf16 v[24:27], v[168:171], v[24:27], v[196:199]
	v_mfma_f32_16x16x32_bf16 v[112:115], v[172:175], v[28:31], v[24:27]
	v_mfma_f32_16x16x32_bf16 v[24:27], v[160:163], v[40:43], v[84:87]
	v_mfma_f32_16x16x32_bf16 v[100:103], v[164:167], v[44:47], v[24:27]
	v_mfma_f32_16x16x32_bf16 v[24:27], v[168:171], v[40:43], v[80:83]
	v_mfma_f32_16x16x32_bf16 v[116:119], v[164:167], v[28:31], v[96:99]
	v_mfma_f32_16x16x32_bf16 v[96:99], v[172:175], v[44:47], v[24:27]
	v_mfma_f32_16x16x32_bf16 v[24:27], v[160:163], v[184:187], v[200:203]
	v_mfma_f32_16x16x32_bf16 v[84:87], v[164:167], v[188:191], v[24:27]
	v_mfma_f32_16x16x32_bf16 v[24:27], v[168:171], v[184:187], v[204:207]
	v_mfma_f32_16x16x32_bf16 v[80:83], v[172:175], v[188:191], v[24:27]
	v_mfma_f32_16x16x32_bf16 v[24:27], v[160:163], v[212:215], v[68:71]
	v_mfma_f32_16x16x32_bf16 v[68:71], v[164:167], v[236:239], v[24:27]
	v_mfma_f32_16x16x32_bf16 v[24:27], v[168:171], v[212:215], v[64:67]
	v_mfma_f32_16x16x32_bf16 v[64:67], v[172:175], v[236:239], v[24:27]
	s_barrier
	ds_read_b128 v[200:203], v226 offset:0
	ds_read_b128 v[204:207], v226 offset:0x400
	ds_read_b128 v[192:195], v226 offset:0x800
	ds_read_b128 v[196:199], v226 offset:0xc00
	ds_read_b128 v[184:187], v226 offset:0x1000
	ds_read_b128 v[188:191], v226 offset:0x1400
	ds_read_b128 v[176:179], v226 offset:0x1800
	ds_read_b128 v[180:183], v226 offset:0x1c00
	s_and_b64 vcc, exec, s[70:71]
	v_lshl_add_u64 v[212:213], s[74:75], 0, v[208:209]
	v_lshl_add_u64 v[214:215], s[72:73], 0, v[208:209]
	s_cbranch_vccz .LBB0_84
	s_mov_b32 m0, s19
	v_lshl_add_u64 v[24:25], v[212:213], 0, s[22:23]
	global_load_lds_dwordx4 v[212:213], off
	s_mov_b32 m0, s30
	s_nop 0
	global_load_lds_dwordx4 v[24:25], off
	s_mov_b32 m0, s3
	v_lshl_add_u64 v[24:25], v[214:215], 0, s[22:23]
	global_load_lds_dwordx4 v[214:215], off
	s_mov_b32 m0, s31
	s_nop 0
	global_load_lds_dwordx4 v[24:25], off
	v_lshl_add_u64 v[24:25], v[212:213], 0, s[24:25]
	s_mov_b32 m0, s50
	s_nop 0
	global_load_lds_dwordx4 v[24:25], off
	v_lshl_add_u64 v[24:25], v[212:213], 0, s[26:27]
	s_mov_b32 m0, s51
	s_nop 0
	global_load_lds_dwordx4 v[24:25], off
	v_lshl_add_u64 v[24:25], v[214:215], 0, s[24:25]
	s_mov_b32 m0, s64
	s_nop 0
	global_load_lds_dwordx4 v[24:25], off
	v_lshl_add_u64 v[24:25], v[214:215], 0, s[26:27]
	s_mov_b32 m0, s65
	s_nop 0
	global_load_lds_dwordx4 v[24:25], off

; #define WAIT_V(n) asm volatile("s_waitcnt vmcnt(%0)" ::"n"(n) : "memory")
; #define SCHED() __builtin_amdgcn_sched_barrier(0)
; #define LGKM(n) asm volatile("s_waitcnt lgkmcnt(%0)" ::"n"(n) : "memory")
; #define STAGE_A(b, h, kt) STAGE_AX(Ag, b, h, kt)
; #define STAGE_B(b, h, kt) STAGE_BX(Bg, b, h, kt)
; #define LDA(b, h) do { const unsigned pa_ = lds0 + SLOTA(b, h) + wr * 8192 + laneoff; _Pragma("unroll") for (int m = 0; m < 4; ++m)   \
;       _Pragma("unroll") for (int k = 0; k < 2; ++k) DSR(At[m][k], pa_, m * 2048 + k * 1024); } while (0)
; #define LDB(dst, b, h) do { const unsigned pb_ = lds0 + SLOTB(b, h) + wc * 4096 + laneoff; _Pragma("unroll") for (int n = 0; n < 2; ++n) \
;       _Pragma("unroll") for (int k = 0; k < 2; ++k) DSR(dst[n][k], pb_, n * 2048 + k * 1024); } while (0)
; #define BAR __builtin_amdgcn_s_barrier()
; #define LGKM(n) asm volatile("s_waitcnt lgkmcnt(%0)" ::"n"(n) : "memory")
; template <int EPI, bool SWP> ...
;     ...
;   for (int t = 0; t < nt - 2; t += 2) {
;     LDB(B0, 0, 0); LDA(0, 0); STAGE_A(1, 1, t + 1);
;     LGKM(8); BAR; LGKM(0); SCHED(); MMA(0, 0, B0); BAR; SCHED();
;     LDB(B1, 0, 1); STAGE_B(0, 0, t + 2);
;     BAR; LGKM(0); SCHED(); MMA(0, 1, B1); BAR; SCHED();
;     LDA(0, 1); STAGE_A(0, 0, t + 2);
;     BAR; LGKM(0); SCHED(); MMA(1, 0, B0); BAR; SCHED();
;     STAGE_B(0, 1, t + 2);
;     WAIT_V(6); BAR; SCHED(); MMA(1, 1, B1); BAR; SCHED();
.LBB0_667:
	ds_read_b128 v[128:131], v219 offset:0
	ds_read_b128 v[132:135], v219 offset:0x400
	ds_read_b128 v[136:139], v219 offset:0x800
	ds_read_b128 v[140:143], v219 offset:0xc00
	ds_read_b128 v[144:147], v220 offset:0
	ds_read_b128 v[148:151], v220 offset:0x400
	ds_read_b128 v[152:155], v220 offset:0x800
	ds_read_b128 v[156:159], v220 offset:0xc00
	ds_read_b128 v[160:163], v220 offset:0x1000
	ds_read_b128 v[164:167], v220 offset:0x1400
	ds_read_b128 v[168:171], v220 offset:0x1800
	v_lshl_add_u64 v[192:193], s[68:69], 0, v[210:211]
	s_mov_b64 s[70:71], 0xc080080
	s_mov_b32 m0, s87
	ds_read_b128 v[172:175], v220 offset:0x1c00
	s_mov_b64 s[70:71], 0xc0c0080
	s_add_u32 s94, s68, 0xc080080
	s_addc_u32 s95, s69, 0
	global_load_lds_dwordx4 v210, s[94:95]
	s_mov_b32 m0, s88
	s_add_u32 s94, s68, 0xc0c0080
	s_addc_u32 s95, s69, 0
	global_load_lds_dwordx4 v210, s[94:95]
	s_waitcnt lgkmcnt(8)
	s_barrier
	s_waitcnt lgkmcnt(0)
	v_mfma_f32_16x16x32_bf16 v[124:127], v[128:131], v[144:147], v[124:127]
	v_mfma_f32_16x16x32_bf16 v[120:123], v[136:139], v[144:147], v[120:123]
	v_mfma_f32_16x16x32_bf16 v[116:119], v[128:131], v[152:155], v[116:119]
	v_mfma_f32_16x16x32_bf16 v[112:115], v[136:139], v[152:155], v[112:115]
	v_mfma_f32_16x16x32_bf16 v[108:111], v[128:131], v[160:163], v[108:111]
	v_mfma_f32_16x16x32_bf16 v[104:107], v[136:139], v[160:163], v[104:107]
	v_mfma_f32_16x16x32_bf16 v[100:103], v[128:131], v[168:171], v[100:103]
	v_mfma_f32_16x16x32_bf16 v[96:99], v[136:139], v[168:171], v[96:99]
	v_mfma_f32_16x16x32_bf16 v[124:127], v[132:135], v[148:151], v[124:127]
	v_mfma_f32_16x16x32_bf16 v[120:123], v[140:143], v[148:151], v[120:123]
	v_mfma_f32_16x16x32_bf16 v[116:119], v[132:135], v[156:159], v[116:119]
	v_mfma_f32_16x16x32_bf16 v[112:115], v[140:143], v[156:159], v[112:115]
	v_mfma_f32_16x16x32_bf16 v[108:111], v[132:135], v[164:167], v[108:111]
	v_mfma_f32_16x16x32_bf16 v[104:107], v[140:143], v[164:167], v[104:107]
	v_mfma_f32_16x16x32_bf16 v[100:103], v[132:135], v[172:175], v[100:103]
	v_mfma_f32_16x16x32_bf16 v[96:99], v[140:143], v[172:175], v[96:99]
	s_barrier
	ds_read_b128 v[176:179], v221 offset:0
	ds_read_b128 v[180:183], v221 offset:0x400
	ds_read_b128 v[184:187], v221 offset:0x800
	v_lshl_add_u64 v[194:195], s[66:67], 0, v[210:211]
	s_mov_b64 s[70:71], 0x2d100100
	s_mov_b32 m0, s75
	ds_read_b128 v[188:191], v221 offset:0xc00
	s_mov_b64 s[70:71], 0x2d140100
	s_add_u32 s94, s66, 0x2d100100
	s_addc_u32 s95, s67, 0
	global_load_lds_dwordx4 v210, s[94:95]
	s_mov_b32 m0, s76
	s_add_u32 s94, s66, 0x2d140100
	s_addc_u32 s95, s67, 0
	global_load_lds_dwordx4 v210, s[94:95]
	s_barrier
	s_waitcnt lgkmcnt(0)
	v_mfma_f32_16x16x32_bf16 v[92:95], v[176:179], v[144:147], v[92:95]
	v_mfma_f32_16x16x32_bf16 v[88:91], v[184:187], v[144:147], v[88:91]
	v_mfma_f32_16x16x32_bf16 v[84:87], v[176:179], v[152:155], v[84:87]
	v_mfma_f32_16x16x32_bf16 v[80:83], v[184:187], v[152:155], v[80:83]
	v_mfma_f32_16x16x32_bf16 v[76:79], v[176:179], v[160:163], v[76:79]
	v_mfma_f32_16x16x32_bf16 v[72:75], v[184:187], v[160:163], v[72:75]
	v_mfma_f32_16x16x32_bf16 v[68:71], v[176:179], v[168:171], v[68:71]
	v_mfma_f32_16x16x32_bf16 v[64:67], v[184:187], v[168:171], v[64:67]
	v_mfma_f32_16x16x32_bf16 v[92:95], v[180:183], v[148:151], v[92:95]
	v_mfma_f32_16x16x32_bf16 v[88:91], v[188:191], v[148:151], v[88:91]
	v_mfma_f32_16x16x32_bf16 v[84:87], v[180:183], v[156:159], v[84:87]
	v_mfma_f32_16x16x32_bf16 v[80:83], v[188:191], v[156:159], v[80:83]
	v_mfma_f32_16x16x32_bf16 v[76:79], v[180:183], v[164:167], v[76:79]
	v_mfma_f32_16x16x32_bf16 v[72:75], v[188:191], v[164:167], v[72:75]
	v_mfma_f32_16x16x32_bf16 v[68:71], v[180:183], v[172:175], v[68:71]
	v_mfma_f32_16x16x32_bf16 v[64:67], v[188:191], v[172:175], v[64:67]
	s_barrier
	ds_read_b128 v[144:147], v222 offset:0
	ds_read_b128 v[148:151], v222 offset:0x400
	ds_read_b128 v[152:155], v222 offset:0x800
	ds_read_b128 v[156:159], v222 offset:0xc00
	ds_read_b128 v[160:163], v222 offset:0x1000
	ds_read_b128 v[164:167], v222 offset:0x1400
	ds_read_b128 v[168:171], v222 offset:0x1800
	s_mov_b64 s[70:71], 0xc000100
	s_mov_b32 m0, s3
	ds_read_b128 v[172:175], v222 offset:0x1c00
	s_mov_b64 s[70:71], 0xc040100
	s_add_u32 s94, s68, 0xc000100
	s_addc_u32 s95, s69, 0
	global_load_lds_dwordx4 v210, s[94:95]
	s_mov_b32 m0, s77
	s_add_u32 s94, s68, 0xc040100
	s_addc_u32 s95, s69, 0
	global_load_lds_dwordx4 v210, s[94:95]
	s_barrier
	s_waitcnt lgkmcnt(0)
	v_mfma_f32_16x16x32_bf16 v[60:63], v[128:131], v[144:147], v[60:63]
	v_mfma_f32_16x16x32_bf16 v[56:59], v[136:139], v[144:147], v[56:59]
	v_mfma_f32_16x16x32_bf16 v[52:55], v[128:131], v[152:155], v[52:55]
	v_mfma_f32_16x16x32_bf16 v[48:51], v[136:139], v[152:155], v[48:51]
	v_mfma_f32_16x16x32_bf16 v[44:47], v[128:131], v[160:163], v[44:47]
	v_mfma_f32_16x16x32_bf16 v[40:43], v[136:139], v[160:163], v[40:43]
	v_mfma_f32_16x16x32_bf16 v[36:39], v[128:131], v[168:171], v[36:39]
	v_mfma_f32_16x16x32_bf16 v[32:35], v[136:139], v[168:171], v[32:35]
	v_mfma_f32_16x16x32_bf16 v[60:63], v[132:135], v[148:151], v[60:63]
	v_mfma_f32_16x16x32_bf16 v[56:59], v[140:143], v[148:151], v[56:59]
	v_mfma_f32_16x16x32_bf16 v[52:55], v[132:135], v[156:159], v[52:55]
	v_mfma_f32_16x16x32_bf16 v[48:51], v[140:143], v[156:159], v[48:51]
	v_mfma_f32_16x16x32_bf16 v[44:47], v[132:135], v[164:167], v[44:47]
	v_mfma_f32_16x16x32_bf16 v[40:43], v[140:143], v[164:167], v[40:43]
	v_mfma_f32_16x16x32_bf16 v[36:39], v[132:135], v[172:175], v[36:39]
	v_mfma_f32_16x16x32_bf16 v[32:35], v[140:143], v[172:175], v[32:35]
	s_barrier
; #define WAIT_V(n) asm volatile("s_waitcnt vmcnt(%0)" ::"n"(n) : "memory")
; #define SCHED() __builtin_amdgcn_sched_barrier(0)
; #define LGKM(n) asm volatile("s_waitcnt lgkmcnt(%0)" ::"n"(n) : "memory")
; #define STAGE_A(b, h, kt) STAGE_AX(Ag, b, h, kt)
; #define STAGE_B(b, h, kt) STAGE_BX(Bg, b, h, kt)
; #define LDA(b, h) do { const unsigned pa_ = lds0 + SLOTA(b, h) + wr * 8192 + laneoff; _Pragma("unroll") for (int m = 0; m < 4; ++m)   \
;       _Pragma("unroll") for (int k = 0; k < 2; ++k) DSR(At[m][k], pa_, m * 2048 + k * 1024); } while (0)
; #define LDB(dst, b, h) do { const unsigned pb_ = lds0 + SLOTB(b, h) + wc * 4096 + laneoff; _Pragma("unroll") for (int n = 0; n < 2; ++n) \
;       _Pragma("unroll") for (int k = 0; k < 2; ++k) DSR(dst[n][k], pb_, n * 2048 + k * 1024); } while (0)
; #define BAR __builtin_amdgcn_s_barrier()
; #define LGKM(n) asm volatile("s_waitcnt lgkmcnt(%0)" ::"n"(n) : "memory")
; template <int EPI, bool SWP> ...
;     ...
;     WAIT_V(6); BAR; SCHED(); MMA(1, 1, B1); BAR; SCHED();
;     LDB(B0, 1, 0); LDA(1, 0); STAGE_A(0, 1, t + 2);
;     LGKM(8); BAR; LGKM(0); SCHED(); MMA(0, 0, B0); BAR; SCHED();
;     LDB(B1, 1, 1); STAGE_B(1, 0, t + 3);
;     BAR; LGKM(0); SCHED(); MMA(0, 1, B1); BAR; SCHED();
;     LDA(1, 1); STAGE_A(1, 0, t + 3);
;     BAR; LGKM(0); SCHED(); MMA(1, 0, B0); BAR; SCHED();
	s_mov_b64 s[70:71], 0x2d180100
	s_mov_b32 m0, s78
	s_mov_b64 s[70:71], 0x2d1c0100
	s_add_u32 s94, s66, 0x2d180100
	s_addc_u32 s95, s67, 0
	global_load_lds_dwordx4 v210, s[94:95]
	s_mov_b32 m0, s79
	s_add_u32 s94, s66, 0x2d1c0100
	s_addc_u32 s95, s67, 0
	global_load_lds_dwordx4 v210, s[94:95]
	s_waitcnt vmcnt(6)
	s_barrier
	v_mfma_f32_16x16x32_bf16 v[28:31], v[176:179], v[144:147], v[28:31]
	v_mfma_f32_16x16x32_bf16 v[24:27], v[184:187], v[144:147], v[24:27]
	v_mfma_f32_16x16x32_bf16 v[20:23], v[176:179], v[152:155], v[20:23]
	v_mfma_f32_16x16x32_bf16 v[16:19], v[184:187], v[152:155], v[16:19]
	v_mfma_f32_16x16x32_bf16 v[12:15], v[176:179], v[160:163], v[12:15]
	v_mfma_f32_16x16x32_bf16 v[8:11], v[184:187], v[160:163], v[8:11]
	v_mfma_f32_16x16x32_bf16 v[4:7], v[176:179], v[168:171], v[4:7]
	v_mfma_f32_16x16x32_bf16 v[0:3], v[184:187], v[168:171], v[0:3]
	v_mfma_f32_16x16x32_bf16 v[28:31], v[180:183], v[148:151], v[28:31]
	v_mfma_f32_16x16x32_bf16 v[24:27], v[188:191], v[148:151], v[24:27]
	v_mfma_f32_16x16x32_bf16 v[20:23], v[180:183], v[156:159], v[20:23]
	v_mfma_f32_16x16x32_bf16 v[16:19], v[188:191], v[156:159], v[16:19]
	v_mfma_f32_16x16x32_bf16 v[12:15], v[180:183], v[164:167], v[12:15]
	v_mfma_f32_16x16x32_bf16 v[8:11], v[188:191], v[164:167], v[8:11]
	v_mfma_f32_16x16x32_bf16 v[4:7], v[180:183], v[172:175], v[4:7]
	v_mfma_f32_16x16x32_bf16 v[0:3], v[188:191], v[172:175], v[0:3]
	s_barrier
	ds_read_b128 v[128:131], v223 offset:0
	ds_read_b128 v[132:135], v223 offset:0x400
	ds_read_b128 v[136:139], v223 offset:0x800
	ds_read_b128 v[140:143], v223 offset:0xc00
	ds_read_b128 v[144:147], v224 offset:0
	ds_read_b128 v[148:151], v224 offset:0x400
	ds_read_b128 v[152:155], v224 offset:0x800
	ds_read_b128 v[156:159], v224 offset:0xc00
	ds_read_b128 v[160:163], v224 offset:0x1000
	ds_read_b128 v[164:167], v224 offset:0x1400
	ds_read_b128 v[168:171], v224 offset:0x1800
	s_mov_b64 s[70:71], 0xc080100
	s_mov_b32 m0, s80
	ds_read_b128 v[172:175], v224 offset:0x1c00
	s_mov_b64 s[70:71], 0xc0c0100
	s_add_u32 s94, s68, 0xc080100
	s_addc_u32 s95, s69, 0
	global_load_lds_dwordx4 v210, s[94:95]
	s_mov_b32 m0, s81
	s_add_u32 s94, s68, 0xc0c0100
	s_addc_u32 s95, s69, 0
	global_load_lds_dwordx4 v210, s[94:95]
	s_waitcnt lgkmcnt(8)
	s_barrier
	s_waitcnt lgkmcnt(0)
	v_mfma_f32_16x16x32_bf16 v[124:127], v[128:131], v[144:147], v[124:127]
	v_mfma_f32_16x16x32_bf16 v[120:123], v[136:139], v[144:147], v[120:123]
	v_mfma_f32_16x16x32_bf16 v[116:119], v[128:131], v[152:155], v[116:119]
	v_mfma_f32_16x16x32_bf16 v[112:115], v[136:139], v[152:155], v[112:115]
	v_mfma_f32_16x16x32_bf16 v[108:111], v[128:131], v[160:163], v[108:111]
	v_mfma_f32_16x16x32_bf16 v[104:107], v[136:139], v[160:163], v[104:107]
	v_mfma_f32_16x16x32_bf16 v[100:103], v[128:131], v[168:171], v[100:103]
	v_mfma_f32_16x16x32_bf16 v[96:99], v[136:139], v[168:171], v[96:99]
	v_mfma_f32_16x16x32_bf16 v[124:127], v[132:135], v[148:151], v[124:127]
	v_mfma_f32_16x16x32_bf16 v[120:123], v[140:143], v[148:151], v[120:123]
	v_mfma_f32_16x16x32_bf16 v[116:119], v[132:135], v[156:159], v[116:119]
	v_mfma_f32_16x16x32_bf16 v[112:115], v[140:143], v[156:159], v[112:115]
	v_mfma_f32_16x16x32_bf16 v[108:111], v[132:135], v[164:167], v[108:111]
	v_mfma_f32_16x16x32_bf16 v[104:107], v[140:143], v[164:167], v[104:107]
	v_mfma_f32_16x16x32_bf16 v[100:103], v[132:135], v[172:175], v[100:103]
	v_mfma_f32_16x16x32_bf16 v[96:99], v[140:143], v[172:175], v[96:99]
	s_barrier
	ds_read_b128 v[176:179], v225 offset:0
	ds_read_b128 v[180:183], v225 offset:0x400
	ds_read_b128 v[184:187], v225 offset:0x800
	s_mov_b64 s[70:71], 0x2d100180
	s_mov_b32 m0, s82
	ds_read_b128 v[188:191], v225 offset:0xc00
	s_mov_b64 s[70:71], 0x2d140180
	s_add_u32 s94, s66, 0x2d100180
	s_addc_u32 s95, s67, 0
	global_load_lds_dwordx4 v210, s[94:95]
	s_mov_b32 m0, s83
	s_add_u32 s94, s66, 0x2d140180
	s_addc_u32 s95, s67, 0
	global_load_lds_dwordx4 v210, s[94:95]
	s_barrier
	s_waitcnt lgkmcnt(0)
	v_mfma_f32_16x16x32_bf16 v[92:95], v[176:179], v[144:147], v[92:95]
	v_mfma_f32_16x16x32_bf16 v[88:91], v[184:187], v[144:147], v[88:91]
	v_mfma_f32_16x16x32_bf16 v[84:87], v[176:179], v[152:155], v[84:87]
	v_mfma_f32_16x16x32_bf16 v[80:83], v[184:187], v[152:155], v[80:83]
	v_mfma_f32_16x16x32_bf16 v[76:79], v[176:179], v[160:163], v[76:79]
	v_mfma_f32_16x16x32_bf16 v[72:75], v[184:187], v[160:163], v[72:75]
	v_mfma_f32_16x16x32_bf16 v[68:71], v[176:179], v[168:171], v[68:71]
	v_mfma_f32_16x16x32_bf16 v[64:67], v[184:187], v[168:171], v[64:67]
	v_mfma_f32_16x16x32_bf16 v[92:95], v[180:183], v[148:151], v[92:95]
	v_mfma_f32_16x16x32_bf16 v[88:91], v[188:191], v[148:151], v[88:91]
	v_mfma_f32_16x16x32_bf16 v[84:87], v[180:183], v[156:159], v[84:87]
	v_mfma_f32_16x16x32_bf16 v[80:83], v[188:191], v[156:159], v[80:83]
	v_mfma_f32_16x16x32_bf16 v[76:79], v[180:183], v[164:167], v[76:79]
	v_mfma_f32_16x16x32_bf16 v[72:75], v[188:191], v[164:167], v[72:75]
	v_mfma_f32_16x16x32_bf16 v[68:71], v[180:183], v[172:175], v[68:71]
	v_mfma_f32_16x16x32_bf16 v[64:67], v[188:191], v[172:175], v[64:67]
	s_barrier
	ds_read_b128 v[144:147], v226 offset:0
	ds_read_b128 v[148:151], v226 offset:0x400
	ds_read_b128 v[152:155], v226 offset:0x800
	ds_read_b128 v[156:159], v226 offset:0xc00
	ds_read_b128 v[160:163], v226 offset:0x1000
	ds_read_b128 v[164:167], v226 offset:0x1400
	ds_read_b128 v[168:171], v226 offset:0x1800
	s_mov_b32 m0, s84
	ds_read_b128 v[172:175], v226 offset:0x1c00
	s_add_u32 s94, s68, s36
	s_addc_u32 s95, s69, s37
	global_load_lds_dwordx4 v210, s[94:95]
	v_lshl_add_u64 v[192:193], v[192:193], 0, s[38:39]
	s_mov_b32 m0, s85
	s_add_u32 s94, s68, s38
	s_addc_u32 s95, s69, s39
	global_load_lds_dwordx4 v210, s[94:95]
	s_barrier
; #define WAIT_V(n) asm volatile("s_waitcnt vmcnt(%0)" ::"n"(n) : "memory")
; #define SCHED() __builtin_amdgcn_sched_barrier(0)
; #define LGKM(n) asm volatile("s_waitcnt lgkmcnt(%0)" ::"n"(n) : "memory")
; #define STAGE_A(b, h, kt) STAGE_AX(Ag, b, h, kt)
; #define STAGE_B(b, h, kt) STAGE_BX(Bg, b, h, kt)
; #define LDA(b, h) do { const unsigned pa_ = lds0 + SLOTA(b, h) + wr * 8192 + laneoff; _Pragma("unroll") for (int m = 0; m < 4; ++m)   \
;       _Pragma("unroll") for (int k = 0; k < 2; ++k) DSR(At[m][k], pa_, m * 2048 + k * 1024); } while (0)
; #define LDB(dst, b, h) do { const unsigned pb_ = lds0 + SLOTB(b, h) + wc * 4096 + laneoff; _Pragma("unroll") for (int n = 0; n < 2; ++n) \
;       _Pragma("unroll") for (int k = 0; k < 2; ++k) DSR(dst[n][k], pb_, n * 2048 + k * 1024); } while (0)
; #define BAR __builtin_amdgcn_s_barrier()
; #define LGKM(n) asm volatile("s_waitcnt lgkmcnt(%0)" ::"n"(n) : "memory")
; template <int EPI, bool SWP> ...
;     ...
;     STAGE_B(1, 1, t + 3);
;     WAIT_V(6); BAR; SCHED(); MMA(1, 1, B1); BAR; SCHED();
;   }
;   { LDB(B0, 0, 0); LDA(0, 0); STAGE_A(1, 1, nt - 1);
;     BAR; LGKM(0); SCHED(); MMA(0, 0, B0); BAR; SCHED();
;     LDB(B1, 0, 1); BAR; LGKM(0); SCHED(); MMA(0, 1, B1); BAR; SCHED();
;     LDA(0, 1); WAIT_V(4); BAR; LGKM(0); SCHED(); MMA(1, 0, B0); MMA(1, 1, B1); BAR; SCHED(); }
	s_waitcnt lgkmcnt(0)
	v_mfma_f32_16x16x32_bf16 v[60:63], v[128:131], v[144:147], v[60:63]
	v_mfma_f32_16x16x32_bf16 v[56:59], v[136:139], v[144:147], v[56:59]
	v_mfma_f32_16x16x32_bf16 v[52:55], v[128:131], v[152:155], v[52:55]
	v_mfma_f32_16x16x32_bf16 v[48:51], v[136:139], v[152:155], v[48:51]
	v_mfma_f32_16x16x32_bf16 v[44:47], v[128:131], v[160:163], v[44:47]
	v_mfma_f32_16x16x32_bf16 v[40:43], v[136:139], v[160:163], v[40:43]
	v_mfma_f32_16x16x32_bf16 v[36:39], v[128:131], v[168:171], v[36:39]
	v_mfma_f32_16x16x32_bf16 v[32:35], v[136:139], v[168:171], v[32:35]
	v_mfma_f32_16x16x32_bf16 v[60:63], v[132:135], v[148:151], v[60:63]
	v_mfma_f32_16x16x32_bf16 v[56:59], v[140:143], v[148:151], v[56:59]
	v_mfma_f32_16x16x32_bf16 v[52:55], v[132:135], v[156:159], v[52:55]
	v_mfma_f32_16x16x32_bf16 v[48:51], v[140:143], v[156:159], v[48:51]
	v_mfma_f32_16x16x32_bf16 v[44:47], v[132:135], v[164:167], v[44:47]
	v_mfma_f32_16x16x32_bf16 v[40:43], v[140:143], v[164:167], v[40:43]
	v_mfma_f32_16x16x32_bf16 v[36:39], v[132:135], v[172:175], v[36:39]
	v_mfma_f32_16x16x32_bf16 v[32:35], v[140:143], v[172:175], v[32:35]
	s_barrier
	s_add_i32 s70, s3, 0x1c000
	s_mov_b32 m0, s70
	s_add_u32 s94, s66, s40
	s_addc_u32 s95, s67, s41
	global_load_lds_dwordx4 v210, s[94:95]
	s_mov_b32 m0, s86
	s_add_u32 s94, s66, s42
	s_addc_u32 s95, s67, s43
	global_load_lds_dwordx4 v210, s[94:95]
	s_waitcnt vmcnt(6)
	s_barrier
	v_mfma_f32_16x16x32_bf16 v[28:31], v[176:179], v[144:147], v[28:31]
	v_mfma_f32_16x16x32_bf16 v[24:27], v[184:187], v[144:147], v[24:27]
	v_mfma_f32_16x16x32_bf16 v[20:23], v[176:179], v[152:155], v[20:23]
	v_mfma_f32_16x16x32_bf16 v[16:19], v[184:187], v[152:155], v[16:19]
	v_mfma_f32_16x16x32_bf16 v[12:15], v[176:179], v[160:163], v[12:15]
	v_mfma_f32_16x16x32_bf16 v[8:11], v[184:187], v[160:163], v[8:11]
	v_mfma_f32_16x16x32_bf16 v[4:7], v[176:179], v[168:171], v[4:7]
	v_mfma_f32_16x16x32_bf16 v[0:3], v[184:187], v[168:171], v[0:3]
	v_mfma_f32_16x16x32_bf16 v[28:31], v[180:183], v[148:151], v[28:31]
	v_mfma_f32_16x16x32_bf16 v[24:27], v[188:191], v[148:151], v[24:27]
	v_mfma_f32_16x16x32_bf16 v[20:23], v[180:183], v[156:159], v[20:23]
	v_mfma_f32_16x16x32_bf16 v[16:19], v[188:191], v[156:159], v[16:19]
	v_mfma_f32_16x16x32_bf16 v[12:15], v[180:183], v[164:167], v[12:15]
	v_mfma_f32_16x16x32_bf16 v[8:11], v[188:191], v[164:167], v[8:11]
	v_mfma_f32_16x16x32_bf16 v[4:7], v[180:183], v[172:175], v[4:7]
	v_mfma_f32_16x16x32_bf16 v[0:3], v[188:191], v[172:175], v[0:3]
	s_add_i32 s1, s1, 2
	s_add_u32 s66, s66, 0x100
	s_addc_u32 s67, s67, 0
	s_add_u32 s68, s68, 0x100
	s_addc_u32 s69, s69, 0
	s_cmp_gt_u32 s1, 27
	s_barrier
	s_cbranch_scc0 .LBB0_667
	ds_read_b128 v[136:139], v219 offset:0
	ds_read_b128 v[140:143], v219 offset:0x400
	ds_read_b128 v[144:147], v219 offset:0x800
	ds_read_b128 v[148:151], v219 offset:0xc00
	ds_read_b128 v[128:131], v220 offset:0
	ds_read_b128 v[132:135], v220 offset:0x400
	ds_read_b128 v[152:155], v220 offset:0x800
	ds_read_b128 v[156:159], v220 offset:0xc00
	ds_read_b128 v[160:163], v220 offset:0x1000
	ds_read_b128 v[164:167], v220 offset:0x1400
	v_lshl_add_u64 v[176:177], s[64:65], 0, v[208:209]
	ds_read_b128 v[168:171], v220 offset:0x1800
	s_mov_b32 m0, s87
	ds_read_b128 v[172:175], v220 offset:0x1c00
	v_lshl_add_u64 v[178:179], v[176:177], 0, s[44:45]
	global_load_lds_dwordx4 v[178:179], off
	v_lshl_add_u64 v[176:177], v[176:177], 0, s[46:47]
	s_mov_b32 m0, s88
	s_ashr_i32 s1, s0, 31
	global_load_lds_dwordx4 v[176:177], off
	s_lshl_b64 s[64:65], s[0:1], 20
	s_add_u32 s64, s24, s64
	s_addc_u32 s65, s25, s65
	s_ashr_i32 s51, s50, 31
	s_barrier
	s_waitcnt lgkmcnt(0)
	s_lshl_b64 s[66:67], s[50:51], 20
	s_add_u32 s66, s30, s66
	s_addc_u32 s67, s31, s67
	v_mfma_f32_16x16x32_bf16 v[124:127], v[136:139], v[128:131], v[124:127]
	v_mfma_f32_16x16x32_bf16 v[120:123], v[144:147], v[128:131], v[120:123]
	v_mfma_f32_16x16x32_bf16 v[116:119], v[136:139], v[152:155], v[116:119]
	v_mfma_f32_16x16x32_bf16 v[112:115], v[144:147], v[152:155], v[112:115]
	v_mfma_f32_16x16x32_bf16 v[108:111], v[136:139], v[160:163], v[108:111]
	v_mfma_f32_16x16x32_bf16 v[104:107], v[144:147], v[160:163], v[104:107]
	v_mfma_f32_16x16x32_bf16 v[100:103], v[136:139], v[168:171], v[100:103]
	v_mfma_f32_16x16x32_bf16 v[96:99], v[144:147], v[168:171], v[96:99]
	v_mfma_f32_16x16x32_bf16 v[124:127], v[140:143], v[132:135], v[124:127]
	v_mfma_f32_16x16x32_bf16 v[120:123], v[148:151], v[132:135], v[120:123]
	v_mfma_f32_16x16x32_bf16 v[116:119], v[140:143], v[156:159], v[116:119]
	v_mfma_f32_16x16x32_bf16 v[112:115], v[148:151], v[156:159], v[112:115]
	v_mfma_f32_16x16x32_bf16 v[176:179], v[140:143], v[164:167], v[108:111]
	v_mfma_f32_16x16x32_bf16 v[180:183], v[148:151], v[164:167], v[104:107]
	v_mfma_f32_16x16x32_bf16 v[100:103], v[140:143], v[172:175], v[100:103]
	v_mfma_f32_16x16x32_bf16 v[96:99], v[148:151], v[172:175], v[96:99]
	s_barrier
	ds_read_b128 v[104:107], v221 offset:0
	ds_read_b128 v[108:111], v221 offset:0x400
	ds_read_b128 v[184:187], v221 offset:0x800
	ds_read_b128 v[188:191], v221 offset:0xc00
	s_barrier
; #define WAIT_V(n) asm volatile("s_waitcnt vmcnt(%0)" ::"n"(n) : "memory")
; #define SCHED() __builtin_amdgcn_sched_barrier(0)
; #define LGKM(n) asm volatile("s_waitcnt lgkmcnt(%0)" ::"n"(n) : "memory")
; #define LDA(b, h) do { const unsigned pa_ = lds0 + SLOTA(b, h) + wr * 8192 + laneoff; _Pragma("unroll") for (int m = 0; m < 4; ++m)   \
;       _Pragma("unroll") for (int k = 0; k < 2; ++k) DSR(At[m][k], pa_, m * 2048 + k * 1024); } while (0)
; #define LDB(dst, b, h) do { const unsigned pb_ = lds0 + SLOTB(b, h) + wc * 4096 + laneoff; _Pragma("unroll") for (int n = 0; n < 2; ++n) \
;       _Pragma("unroll") for (int k = 0; k < 2; ++k) DSR(dst[n][k], pb_, n * 2048 + k * 1024); } while (0)
; #define BAR __builtin_amdgcn_s_barrier()
; #define LGKM(n) asm volatile("s_waitcnt lgkmcnt(%0)" ::"n"(n) : "memory")
; template <int EPI, bool SWP> ...
;     ...
;     LDA(0, 1); WAIT_V(4); BAR; LGKM(0); SCHED(); MMA(1, 0, B0); MMA(1, 1, B1); BAR; SCHED(); }
;   { LDB(B0, 1, 0); LDA(1, 0); WAIT_V(2); BAR; LGKM(0); SCHED(); MMA(0, 0, B0); BAR; SCHED();
	s_waitcnt lgkmcnt(0)
	v_mfma_f32_16x16x32_bf16 v[92:95], v[104:107], v[128:131], v[92:95]
	v_mfma_f32_16x16x32_bf16 v[88:91], v[184:187], v[128:131], v[88:91]
	v_mfma_f32_16x16x32_bf16 v[84:87], v[104:107], v[152:155], v[84:87]
	v_mfma_f32_16x16x32_bf16 v[80:83], v[184:187], v[152:155], v[80:83]
	v_mfma_f32_16x16x32_bf16 v[76:79], v[104:107], v[160:163], v[76:79]
	v_mfma_f32_16x16x32_bf16 v[72:75], v[184:187], v[160:163], v[72:75]
	v_mfma_f32_16x16x32_bf16 v[68:71], v[104:107], v[168:171], v[68:71]
	v_mfma_f32_16x16x32_bf16 v[64:67], v[184:187], v[168:171], v[64:67]
	v_mfma_f32_16x16x32_bf16 v[192:195], v[108:111], v[132:135], v[92:95]
	v_mfma_f32_16x16x32_bf16 v[196:199], v[188:191], v[132:135], v[88:91]
	v_mfma_f32_16x16x32_bf16 v[84:87], v[108:111], v[156:159], v[84:87]
	v_mfma_f32_16x16x32_bf16 v[80:83], v[188:191], v[156:159], v[80:83]
	v_mfma_f32_16x16x32_bf16 v[200:203], v[108:111], v[164:167], v[76:79]
	v_mfma_f32_16x16x32_bf16 v[204:207], v[188:191], v[164:167], v[72:75]
	v_mfma_f32_16x16x32_bf16 v[68:71], v[108:111], v[172:175], v[68:71]
	v_mfma_f32_16x16x32_bf16 v[64:67], v[188:191], v[172:175], v[64:67]
	s_barrier
	ds_read_b128 v[72:75], v222 offset:0
	ds_read_b128 v[76:79], v222 offset:0x400
	ds_read_b128 v[88:91], v222 offset:0x800
	ds_read_b128 v[92:95], v222 offset:0xc00
	ds_read_b128 v[152:155], v222 offset:0x1000
	ds_read_b128 v[156:159], v222 offset:0x1400
	ds_read_b128 v[160:163], v222 offset:0x1800
	ds_read_b128 v[164:167], v222 offset:0x1c00
	s_waitcnt vmcnt(4)
	s_barrier
	s_waitcnt lgkmcnt(0)
	v_mfma_f32_16x16x32_bf16 v[60:63], v[136:139], v[72:75], v[60:63]
	v_mfma_f32_16x16x32_bf16 v[56:59], v[144:147], v[72:75], v[56:59]
	v_mfma_f32_16x16x32_bf16 v[52:55], v[136:139], v[88:91], v[52:55]
	v_mfma_f32_16x16x32_bf16 v[48:51], v[144:147], v[88:91], v[48:51]
	v_mfma_f32_16x16x32_bf16 v[44:47], v[136:139], v[152:155], v[44:47]
	v_mfma_f32_16x16x32_bf16 v[40:43], v[144:147], v[152:155], v[40:43]
	v_mfma_f32_16x16x32_bf16 v[36:39], v[136:139], v[160:163], v[36:39]
	v_mfma_f32_16x16x32_bf16 v[32:35], v[144:147], v[160:163], v[32:35]
	v_mfma_f32_16x16x32_bf16 v[60:63], v[140:143], v[76:79], v[60:63]
	v_mfma_f32_16x16x32_bf16 v[56:59], v[148:151], v[76:79], v[56:59]
	v_mfma_f32_16x16x32_bf16 v[52:55], v[140:143], v[92:95], v[52:55]
	v_mfma_f32_16x16x32_bf16 v[48:51], v[148:151], v[92:95], v[48:51]
	v_mfma_f32_16x16x32_bf16 v[128:131], v[140:143], v[156:159], v[44:47]
	v_mfma_f32_16x16x32_bf16 v[132:135], v[148:151], v[156:159], v[40:43]
	v_mfma_f32_16x16x32_bf16 v[36:39], v[140:143], v[164:167], v[36:39]
	v_mfma_f32_16x16x32_bf16 v[32:35], v[148:151], v[164:167], v[32:35]
	v_mfma_f32_16x16x32_bf16 v[28:31], v[104:107], v[72:75], v[28:31]
	v_mfma_f32_16x16x32_bf16 v[24:27], v[184:187], v[72:75], v[24:27]
	v_mfma_f32_16x16x32_bf16 v[20:23], v[104:107], v[88:91], v[20:23]
	v_mfma_f32_16x16x32_bf16 v[16:19], v[184:187], v[88:91], v[16:19]
	v_mfma_f32_16x16x32_bf16 v[12:15], v[104:107], v[152:155], v[12:15]
	v_mfma_f32_16x16x32_bf16 v[8:11], v[184:187], v[152:155], v[8:11]
	v_mfma_f32_16x16x32_bf16 v[4:7], v[104:107], v[160:163], v[4:7]
	v_mfma_f32_16x16x32_bf16 v[0:3], v[184:187], v[160:163], v[0:3]
	v_mfma_f32_16x16x32_bf16 v[136:139], v[108:111], v[76:79], v[28:31]
	v_mfma_f32_16x16x32_bf16 v[140:143], v[188:191], v[76:79], v[24:27]
	v_mfma_f32_16x16x32_bf16 v[20:23], v[108:111], v[92:95], v[20:23]
	v_mfma_f32_16x16x32_bf16 v[16:19], v[188:191], v[92:95], v[16:19]
	v_mfma_f32_16x16x32_bf16 v[144:147], v[108:111], v[156:159], v[12:15]
	v_mfma_f32_16x16x32_bf16 v[148:151], v[188:191], v[156:159], v[8:11]
	v_mfma_f32_16x16x32_bf16 v[4:7], v[108:111], v[164:167], v[4:7]
	v_mfma_f32_16x16x32_bf16 v[0:3], v[188:191], v[164:167], v[0:3]
	s_barrier
	ds_read_b128 v[8:11], v223 offset:0
	ds_read_b128 v[12:15], v223 offset:0x400
	ds_read_b128 v[152:155], v223 offset:0x800
	ds_read_b128 v[156:159], v223 offset:0xc00
	ds_read_b128 v[24:27], v224 offset:0
	ds_read_b128 v[28:31], v224 offset:0x400
	ds_read_b128 v[40:43], v224 offset:0x800
	ds_read_b128 v[44:47], v224 offset:0xc00
	ds_read_b128 v[184:187], v224 offset:0x1000
	ds_read_b128 v[188:191], v224 offset:0x1400
	ds_read_b128 v[212:215], v224 offset:0x1800
	ds_read_b128 v[236:239], v224 offset:0x1c00
	s_waitcnt vmcnt(2)
	s_barrier
; #define WAIT_V(n) asm volatile("s_waitcnt vmcnt(%0)" ::"n"(n) : "memory")
; #define SCHED() __builtin_amdgcn_sched_barrier(0)
; #define LGKM(n) asm volatile("s_waitcnt lgkmcnt(%0)" ::"n"(n) : "memory")
; #define STAGE_AX(AG, b, h, kt) do { _Pragma("unroll") for (int i = 0; i < 2; ++i)                                    \
;       __builtin_amdgcn_global_load_lds((const unsigned*)(((AG) + ((size_t)(kt) * (BK * 2) + (size_t)((h) * 2 + i) * 128 * lda)) + aoff), \
;                                        (unsigned*)(shm + SLOTA(b, h) + wid * 1024 + i * 8192), 16, 0, 0); } while (0)
; #define STAGE_BX(BG, b, h, kt) do { _Pragma("unroll") for (int i = 0; i < 2; ++i)                                    \
;       __builtin_amdgcn_global_load_lds((const unsigned*)(((BG) + ((size_t)(kt) * (BK * 2) + (size_t)((h) * 2 + i) * 128 * K)) + boff),   \
;                                        (unsigned*)(shm + SLOTB(b, h) + wid * 1024 + i * 8192), 16, 0, 0); } while (0)
; #define LDA(b, h) do { const unsigned pa_ = lds0 + SLOTA(b, h) + wr * 8192 + laneoff; _Pragma("unroll") for (int m = 0; m < 4; ++m)   \
;       _Pragma("unroll") for (int k = 0; k < 2; ++k) DSR(At[m][k], pa_, m * 2048 + k * 1024); } while (0)
; #define LDB(dst, b, h) do { const unsigned pb_ = lds0 + SLOTB(b, h) + wc * 4096 + laneoff; _Pragma("unroll") for (int n = 0; n < 2; ++n) \
;       _Pragma("unroll") for (int k = 0; k < 2; ++k) DSR(dst[n][k], pb_, n * 2048 + k * 1024); } while (0)
; #define BAR __builtin_amdgcn_s_barrier()
; #define LGKM(n) asm volatile("s_waitcnt lgkmcnt(%0)" ::"n"(n) : "memory")
; template <int EPI, bool SWP> ...
;     ...
;   { LDB(B0, 1, 0); LDA(1, 0); WAIT_V(2); BAR; LGKM(0); SCHED(); MMA(0, 0, B0); BAR; SCHED();
;     LDB(B1, 1, 1); WAIT_V(0); BAR; LGKM(0); SCHED(); MMA(0, 1, B1); BAR; SCHED();
;     LDA(1, 1);
;     if (has_next) { STAGE_BX(Bg_n, 0, 0, 0); STAGE_AX(Ag_n, 0, 0, 0); STAGE_BX(Bg_n, 0, 1, 0); STAGE_AX(Ag_n, 0, 1, 0); }
	s_waitcnt lgkmcnt(0)
	v_mfma_f32_16x16x32_bf16 v[72:75], v[8:11], v[24:27], v[124:127]
	v_mfma_f32_16x16x32_bf16 v[124:127], v[12:15], v[28:31], v[72:75]
	v_mfma_f32_16x16x32_bf16 v[72:75], v[152:155], v[24:27], v[120:123]
	v_mfma_f32_16x16x32_bf16 v[120:123], v[156:159], v[28:31], v[72:75]
	v_mfma_f32_16x16x32_bf16 v[72:75], v[8:11], v[40:43], v[116:119]
	v_mfma_f32_16x16x32_bf16 v[108:111], v[12:15], v[44:47], v[72:75]
	v_mfma_f32_16x16x32_bf16 v[72:75], v[152:155], v[40:43], v[112:115]
	v_mfma_f32_16x16x32_bf16 v[104:107], v[156:159], v[44:47], v[72:75]
	v_mfma_f32_16x16x32_bf16 v[72:75], v[8:11], v[184:187], v[176:179]
	v_mfma_f32_16x16x32_bf16 v[92:95], v[12:15], v[188:191], v[72:75]
	v_mfma_f32_16x16x32_bf16 v[72:75], v[152:155], v[184:187], v[180:183]
	v_mfma_f32_16x16x32_bf16 v[88:91], v[156:159], v[188:191], v[72:75]
	v_mfma_f32_16x16x32_bf16 v[72:75], v[8:11], v[212:215], v[100:103]
	v_mfma_f32_16x16x32_bf16 v[76:79], v[12:15], v[236:239], v[72:75]
	v_mfma_f32_16x16x32_bf16 v[72:75], v[152:155], v[212:215], v[96:99]
	v_mfma_f32_16x16x32_bf16 v[72:75], v[156:159], v[236:239], v[72:75]
	s_barrier
	ds_read_b128 v[160:163], v225 offset:0
	ds_read_b128 v[164:167], v225 offset:0x400
	ds_read_b128 v[168:171], v225 offset:0x800
	ds_read_b128 v[172:175], v225 offset:0xc00
	s_waitcnt vmcnt(0)
	s_barrier
	s_waitcnt lgkmcnt(0)
	v_mfma_f32_16x16x32_bf16 v[96:99], v[160:163], v[24:27], v[192:195]
	v_mfma_f32_16x16x32_bf16 v[24:27], v[168:171], v[24:27], v[196:199]
	v_mfma_f32_16x16x32_bf16 v[112:115], v[172:175], v[28:31], v[24:27]
	v_mfma_f32_16x16x32_bf16 v[24:27], v[160:163], v[40:43], v[84:87]
	v_mfma_f32_16x16x32_bf16 v[100:103], v[164:167], v[44:47], v[24:27]
	v_mfma_f32_16x16x32_bf16 v[24:27], v[168:171], v[40:43], v[80:83]
	v_mfma_f32_16x16x32_bf16 v[116:119], v[164:167], v[28:31], v[96:99]
	v_mfma_f32_16x16x32_bf16 v[96:99], v[172:175], v[44:47], v[24:27]
	v_mfma_f32_16x16x32_bf16 v[24:27], v[160:163], v[184:187], v[200:203]
	v_mfma_f32_16x16x32_bf16 v[84:87], v[164:167], v[188:191], v[24:27]
	v_mfma_f32_16x16x32_bf16 v[24:27], v[168:171], v[184:187], v[204:207]
	v_mfma_f32_16x16x32_bf16 v[80:83], v[172:175], v[188:191], v[24:27]
	v_mfma_f32_16x16x32_bf16 v[24:27], v[160:163], v[212:215], v[68:71]
	v_mfma_f32_16x16x32_bf16 v[68:71], v[164:167], v[236:239], v[24:27]
	v_mfma_f32_16x16x32_bf16 v[24:27], v[168:171], v[212:215], v[64:67]
	v_mfma_f32_16x16x32_bf16 v[64:67], v[172:175], v[236:239], v[24:27]
	s_barrier
	ds_read_b128 v[200:203], v226 offset:0
	ds_read_b128 v[204:207], v226 offset:0x400
	ds_read_b128 v[192:195], v226 offset:0x800
	ds_read_b128 v[196:199], v226 offset:0xc00
	ds_read_b128 v[184:187], v226 offset:0x1000
	ds_read_b128 v[188:191], v226 offset:0x1400
	ds_read_b128 v[176:179], v226 offset:0x1800
	ds_read_b128 v[180:183], v226 offset:0x1c00
	s_and_b64 vcc, exec, s[62:63]
	v_lshl_add_u64 v[212:213], s[66:67], 0, v[208:209]
	v_lshl_add_u64 v[214:215], s[64:65], 0, v[208:209]
	s_cbranch_vccz .LBB0_670
	s_mov_b32 m0, s75
	v_lshl_add_u64 v[24:25], v[212:213], 0, s[12:13]
	global_load_lds_dwordx4 v[212:213], off
	s_mov_b32 m0, s76
	s_nop 0
	global_load_lds_dwordx4 v[24:25], off
	s_mov_b32 m0, s3
	v_lshl_add_u64 v[24:25], v[214:215], 0, s[12:13]
	global_load_lds_dwordx4 v[214:215], off
	s_mov_b32 m0, s77
	s_nop 0
	global_load_lds_dwordx4 v[24:25], off
	v_lshl_add_u64 v[24:25], v[212:213], 0, s[14:15]
	s_mov_b32 m0, s78
	s_nop 0
	global_load_lds_dwordx4 v[24:25], off
	v_lshl_add_u64 v[24:25], v[212:213], 0, s[16:17]
	s_mov_b32 m0, s79
	s_nop 0
	global_load_lds_dwordx4 v[24:25], off
	v_lshl_add_u64 v[24:25], v[214:215], 0, s[14:15]
	s_mov_b32 m0, s80
	s_nop 0
	global_load_lds_dwordx4 v[24:25], off
	v_lshl_add_u64 v[24:25], v[214:215], 0, s[16:17]
	s_mov_b32 m0, s81
	s_nop 0
	global_load_lds_dwordx4 v[24:25], off
